# hand-written SwiGLU epilogue arithmetic in both FFN-in phases (4 VALU + 2 transcendental per element, f32) on top of v4
# speedup vs baseline: 1.0069x; 1.0042x over previous
; __device__ __forceinline__ void wave_row_rs(const float* SS, int base, int fr, int fq, float (&rs)[2][4]) {
;     const int L = fq * 16 + fr; float mine[2]; f32x4 p[2][4];
; #pragma unroll
;     for (int ai = 0; ai < 2; ++ai) { const f32x4* q = (const f32x4*)(SS + (size_t)(base + ai * HALF + L) * 16);
; #pragma unroll
;         for (int j = 0; j < 4; ++j) p[ai][j] = q[j]; }
; #pragma unroll
;     for (int ai = 0; ai < 2; ++ai) { const f32x4 a = p[ai][0], b = p[ai][1], c = p[ai][2], d = p[ai][3];
;         const float s = ((a[0] + a[1]) + (a[2] + a[3])) + ((b[0] + b[1]) + (b[2] + b[3])) + ((c[0] + c[1]) + (c[2] + c[3])) + ((d[0] + d[1]) + (d[2] + d[3]));
;         mine[ai] = 1.0f / sqrtf(s * (1.0f / 1024.0f) + 1e-6f); }
; #pragma unroll
;     for (int ai = 0; ai < 2; ++ai)
; #pragma unroll
;         for (int m = 0; m < 4; ++m) rs[ai][m] = __int_as_float(__builtin_amdgcn_ds_bpermute((m * 16 + fr) * 4, __float_as_int(mine[ai])));
; }
;     __device__ __forceinline__ void operator()(const f32x4 (&acc)[2][2][4][2], const Unit& u, int wr, int wc, int fr, int fq) const {
;         const int row0 = u.pm * BM + wr * 64 + fr, col0 = u.pn * HALF + wc * 32 + 8 * fq;
;         float rsv[2][4]; wave_row_rs(SS, u.pm * BM + wr * 64, fr, fq, rsv);
.LBB0_1203:
	s_lshl_b32 s0, s6, 8
	s_add_i32 s0, s0, s49
	v_or_b32_e32 v144, s0, v149
	v_ashrrev_i32_e32 v145, 31, v144
	v_lshlrev_b64 v[160:161], 6, v[144:145]
	v_lshl_add_u64 v[172:173], s[22:23], 0, v[160:161]
	v_add_u32_e32 v144, 0x80, v144
	global_load_dwordx4 v[160:163], v[172:173], off
	global_load_dwordx4 v[164:167], v[172:173], off offset:16
	global_load_dwordx4 v[168:171], v[172:173], off offset:32
	s_nop 0
	global_load_dwordx4 v[172:175], v[172:173], off offset:48
	v_ashrrev_i32_e32 v145, 31, v144
	v_lshlrev_b64 v[144:145], 6, v[144:145]
	v_lshl_add_u64 v[144:145], s[22:23], 0, v[144:145]
	global_load_dwordx4 v[176:179], v[144:145], off
	global_load_dwordx4 v[180:183], v[144:145], off offset:16
	global_load_dwordx4 v[184:187], v[144:145], off offset:32
	global_load_dwordx4 v[188:191], v[144:145], off offset:48
	v_lshl_or_b32 v144, s7, 7, v153
	v_or_b32_e32 v159, s0, v146
	s_waitcnt vmcnt(0)
	v_mov_b32_e32 v192, v161
	v_mov_b32_e32 v193, v162
	v_mov_b32_e32 v161, v163
	v_mov_b32_e32 v162, v165
	v_mov_b32_e32 v163, v166
	v_mov_b32_e32 v165, v167
	v_add_f32_e32 v166, v168, v169
	v_add_f32_e32 v168, v170, v171
	v_mov_b32_e32 v167, v174
	v_mov_b32_e32 v169, v175
	v_pk_add_f32 v[160:161], v[192:193], v[160:161]
	v_pk_add_f32 v[162:163], v[162:163], v[164:165]
	v_pk_add_f32 v[164:165], v[166:167], v[168:169]
	v_mov_b32_e32 v166, v177
	v_mov_b32_e32 v167, v178
	v_mov_b32_e32 v177, v179
	v_mov_b32_e32 v168, v181
	v_mov_b32_e32 v169, v182
	v_mov_b32_e32 v181, v183
	v_pk_add_f32 v[160:161], v[160:161], v[160:161] op_sel:[0,1] op_sel_hi:[1,0]
	v_pk_add_f32 v[162:163], v[162:163], v[162:163] op_sel:[0,1] op_sel_hi:[1,0]
	v_pk_add_f32 v[166:167], v[166:167], v[176:177]
	v_pk_add_f32 v[168:169], v[168:169], v[180:181]
	v_mov_b32_e32 v161, v172
	v_mov_b32_e32 v163, v173
	v_pk_add_f32 v[166:167], v[166:167], v[166:167] op_sel:[0,1] op_sel_hi:[1,0]
	v_pk_add_f32 v[168:169], v[168:169], v[168:169] op_sel:[0,1] op_sel_hi:[1,0]
	v_pk_add_f32 v[160:161], v[160:161], v[162:163]
	v_add_f32_e32 v170, v184, v185
	v_add_f32_e32 v174, v186, v187
	v_mov_b32_e32 v171, v190
	v_mov_b32_e32 v175, v191
	v_mov_b32_e32 v167, v188
	v_mov_b32_e32 v169, v189
	v_pk_add_f32 v[160:161], v[160:161], v[164:165]
	v_pk_add_f32 v[170:171], v[170:171], v[174:175]
	v_pk_add_f32 v[162:163], v[166:167], v[168:169]
	v_add_f32_e32 v145, v160, v161
	v_pk_add_f32 v[160:161], v[162:163], v[170:171]
	v_fmamk_f32 v145, v145, 0x3a800000, v157
	v_add_f32_e32 v160, v160, v161
	v_mul_f32_e32 v161, 0x4f800000, v145
	v_cmp_gt_f32_e32 vcc, s74, v145
	v_fmamk_f32 v160, v160, 0x3a800000, v157
	v_cmp_gt_f32_e64 s[6:7], s74, v160
	v_cndmask_b32_e32 v145, v145, v161, vcc
	v_mul_f32_e32 v161, 0x4f800000, v160
	v_sqrt_f32_e32 v162, v145
	v_cndmask_b32_e64 v160, v160, v161, s[6:7]
	v_sqrt_f32_e32 v161, v160
	v_add_u32_e32 v163, -1, v162
	v_add_u32_e32 v164, 1, v162
	v_fma_f32 v165, -v163, v162, v145
	v_fma_f32 v166, -v164, v162, v145
	v_add_u32_e32 v167, -1, v161
	v_cmp_ge_f32_e64 s[8:9], 0, v165
	v_add_u32_e32 v168, 1, v161
	v_fma_f32 v165, -v168, v161, v160
	v_cndmask_b32_e64 v162, v162, v163, s[8:9]
	v_fma_f32 v163, -v167, v161, v160
	v_cmp_lt_f32_e64 s[8:9], 0, v166
	s_nop 1
	v_cndmask_b32_e64 v162, v162, v164, s[8:9]
	v_cmp_ge_f32_e64 s[8:9], 0, v163
	v_mul_f32_e32 v163, 0x37800000, v162
	v_cndmask_b32_e32 v162, v162, v163, vcc
	v_cndmask_b32_e64 v161, v161, v167, s[8:9]
	v_cmp_lt_f32_e64 s[8:9], 0, v165
	v_cmp_class_f32_e32 vcc, v145, v158
	s_nop 0
	v_cndmask_b32_e64 v161, v161, v168, s[8:9]
	v_mul_f32_e32 v163, 0x37800000, v161
	v_cndmask_b32_e32 v145, v162, v145, vcc
	v_cndmask_b32_e64 v161, v161, v163, s[6:7]
	v_div_scale_f32 v162, s[0:1], v145, v145, 1.0
	v_cmp_class_f32_e64 s[6:7], v160, v158
	v_div_scale_f32 v163, vcc, 1.0, v145, 1.0
	s_nop 0
	v_cndmask_b32_e64 v160, v161, v160, s[6:7]
	v_rcp_f32_e32 v161, v162
	v_div_scale_f32 v164, s[0:1], v160, v160, 1.0
	v_rcp_f32_e32 v165, v164
	v_fma_f32 v167, -v162, v161, 1.0
	v_fmac_f32_e32 v161, v167, v161
	v_mul_f32_e32 v168, v163, v161
	v_fma_f32 v167, -v164, v165, 1.0
	v_fmac_f32_e32 v165, v167, v165
	v_fma_f32 v167, -v162, v168, v163
	v_div_scale_f32 v166, s[6:7], 1.0, v160, 1.0
	v_fmac_f32_e32 v168, v167, v161
	v_mul_f32_e32 v169, v166, v165
	v_fma_f32 v162, -v162, v168, v163
	v_fma_f32 v167, -v164, v169, v166
	v_div_fmas_f32 v161, v162, v161, v168
	v_fmac_f32_e32 v169, v167, v165
	v_div_fixup_f32 v145, v161, v145, 1.0
	v_fma_f32 v162, -v164, v169, v166
	ds_bpermute_b32 v164, v147, v145
	s_mov_b64 vcc, s[6:7]
	v_div_fmas_f32 v161, v162, v165, v169
	ds_bpermute_b32 v168, v150, v145
	ds_bpermute_b32 v169, v151, v145
	ds_bpermute_b32 v170, v152, v145
	v_div_fixup_f32 v160, v161, v160, 1.0
	v_ashrrev_i32_e32 v145, 31, v144
	ds_bpermute_b32 v163, v147, v160
	ds_bpermute_b32 v162, v150, v160
	ds_bpermute_b32 v161, v151, v160
	ds_bpermute_b32 v232, v152, v160
	v_mov_b64_e32 v[204:205], s[24:25]
	v_lshlrev_b64 v[206:207], 1, v[144:145]
	s_andn2_b64 vcc, exec, s[4:5]
	s_waitcnt lgkmcnt(7)
; __device__ __forceinline__ unsigned cvt_pk_bf16(float lo, float hi) { unsigned r; asm volatile("v_cvt_pk_bf16_f32 %0, %1, %2" : "=v"(r) : "v"(lo), "v"(hi)); return r; }
;     __device__ __forceinline__ void operator()(const f32x4 (&acc)[2][2][4][2], const Unit& u, int wr, int wc, int fr, int fq) const {
;     ...
;             for (int m = 0; m < 4; ++m) { const int row = row0 + ai * HALF + m * 16; const float rs = rsv[ai][m];
;                 float o[8];
;                 const float rs2 = -1.4426950408889634f * rs, rq = rs * rs;
; #pragma unroll
;                 for (int n = 0; n < 2; ++n)
; #pragma unroll
;                     for (int i = 0; i < 4; ++i) { const float a = acc[ai][0][m][n][i], b = acc[ai][1][m][n][i];
;                         const float e = __builtin_amdgcn_exp2f(a * rs2); o[n * 4 + i] = (a * b) * (rq * __builtin_amdgcn_rcpf(1.0f + e)); }
;                 u32x4 w; w.x = cvt_pk_bf16(o[0], o[1]); w.y = cvt_pk_bf16(o[2], o[3]); w.z = cvt_pk_bf16(o[4], o[5]); w.w = cvt_pk_bf16(o[6], o[7]);
;                 *(u32x4*)(O + (size_t)row * ldc + col0) = w; }
	v_mul_f32_e32 v172, 0xbfb8aa3b, v164
	v_mul_f32_e32 v173, v164, v164
	v_rcp_f32_e32 v173, v173
	v_mul_f32_e32 v176, v124, v172
	v_mul_f32_e32 v177, v125, v172
	v_mul_f32_e32 v178, v126, v172
	v_mul_f32_e32 v179, v127, v172
	v_mul_f32_e32 v180, v116, v172
	v_mul_f32_e32 v181, v117, v172
	v_mul_f32_e32 v182, v118, v172
	v_mul_f32_e32 v183, v119, v172
	v_exp_f32_e32 v176, v176
	v_exp_f32_e32 v177, v177
	v_exp_f32_e32 v178, v178
	v_exp_f32_e32 v179, v179
	v_exp_f32_e32 v180, v180
	v_exp_f32_e32 v181, v181
	v_exp_f32_e32 v182, v182
	v_exp_f32_e32 v183, v183
	v_mul_f32_e32 v184, v124, v120
	v_mul_f32_e32 v185, v125, v121
	v_mul_f32_e32 v186, v126, v122
	v_mul_f32_e32 v187, v127, v123
	v_mul_f32_e32 v188, v116, v112
	v_mul_f32_e32 v189, v117, v113
	v_mul_f32_e32 v190, v118, v114
	v_mul_f32_e32 v191, v119, v115
	v_fma_f32 v176, v176, v173, v173
	v_fma_f32 v177, v177, v173, v173
	v_fma_f32 v178, v178, v173, v173
	v_fma_f32 v179, v179, v173, v173
	v_fma_f32 v180, v180, v173, v173
	v_fma_f32 v181, v181, v173, v173
	v_fma_f32 v182, v182, v173, v173
	v_fma_f32 v183, v183, v173, v173
	v_rcp_f32_e32 v176, v176
	v_rcp_f32_e32 v177, v177
	v_rcp_f32_e32 v178, v178
	v_rcp_f32_e32 v179, v179
	v_rcp_f32_e32 v180, v180
	v_rcp_f32_e32 v181, v181
	v_rcp_f32_e32 v182, v182
	v_rcp_f32_e32 v183, v183
	v_add_u32_e32 v200, 0, v159
	v_mad_i64_i32 v[200:201], s[0:1], v200, s75, v[204:205]
	v_mul_f32_e32 v184, v184, v176
	v_mul_f32_e32 v185, v185, v177
	v_mul_f32_e32 v186, v186, v178
	v_mul_f32_e32 v187, v187, v179
	v_mul_f32_e32 v188, v188, v180
	v_mul_f32_e32 v189, v189, v181
	v_mul_f32_e32 v190, v190, v182
	v_mul_f32_e32 v191, v191, v183
	v_lshl_add_u64 v[200:201], v[200:201], 0, v[206:207]
	v_cvt_pk_bf16_f32 v192, v184, v185
	v_cvt_pk_bf16_f32 v193, v186, v187
	v_cvt_pk_bf16_f32 v194, v188, v189
	v_cvt_pk_bf16_f32 v195, v190, v191
	global_store_dwordx4 v[200:201], v[192:195], off
	s_waitcnt lgkmcnt(6)
	v_mul_f32_e32 v172, 0xbfb8aa3b, v168
	v_mul_f32_e32 v173, v168, v168
	v_rcp_f32_e32 v173, v173
	v_mul_f32_e32 v176, v108, v172
	v_mul_f32_e32 v177, v109, v172
	v_mul_f32_e32 v178, v110, v172
	v_mul_f32_e32 v179, v111, v172
	v_mul_f32_e32 v180, v100, v172
	v_mul_f32_e32 v181, v101, v172
	v_mul_f32_e32 v182, v102, v172
	v_mul_f32_e32 v183, v103, v172
	v_exp_f32_e32 v176, v176
	v_exp_f32_e32 v177, v177
	v_exp_f32_e32 v178, v178
	v_exp_f32_e32 v179, v179
	v_exp_f32_e32 v180, v180
	v_exp_f32_e32 v181, v181
	v_exp_f32_e32 v182, v182
	v_exp_f32_e32 v183, v183
	v_mul_f32_e32 v184, v108, v104
	v_mul_f32_e32 v185, v109, v105
	v_mul_f32_e32 v186, v110, v106
	v_mul_f32_e32 v187, v111, v107
	v_mul_f32_e32 v188, v100, v96
	v_mul_f32_e32 v189, v101, v97
	v_mul_f32_e32 v190, v102, v98
	v_mul_f32_e32 v191, v103, v99
	v_fma_f32 v176, v176, v173, v173
	v_fma_f32 v177, v177, v173, v173
	v_fma_f32 v178, v178, v173, v173
	v_fma_f32 v179, v179, v173, v173
	v_fma_f32 v180, v180, v173, v173
	v_fma_f32 v181, v181, v173, v173
	v_fma_f32 v182, v182, v173, v173
	v_fma_f32 v183, v183, v173, v173
	v_rcp_f32_e32 v176, v176
	v_rcp_f32_e32 v177, v177
	v_rcp_f32_e32 v178, v178
	v_rcp_f32_e32 v179, v179
	v_rcp_f32_e32 v180, v180
	v_rcp_f32_e32 v181, v181
	v_rcp_f32_e32 v182, v182
	v_rcp_f32_e32 v183, v183
	v_add_u32_e32 v202, 16, v159
	v_mad_i64_i32 v[202:203], s[0:1], v202, s75, v[204:205]
	v_mul_f32_e32 v184, v184, v176
	v_mul_f32_e32 v185, v185, v177
	v_mul_f32_e32 v186, v186, v178
	v_mul_f32_e32 v187, v187, v179
	v_mul_f32_e32 v188, v188, v180
	v_mul_f32_e32 v189, v189, v181
	v_mul_f32_e32 v190, v190, v182
	v_mul_f32_e32 v191, v191, v183
	v_lshl_add_u64 v[202:203], v[202:203], 0, v[206:207]
	v_cvt_pk_bf16_f32 v196, v184, v185
	v_cvt_pk_bf16_f32 v197, v186, v187
	v_cvt_pk_bf16_f32 v198, v188, v189
	v_cvt_pk_bf16_f32 v199, v190, v191
	global_store_dwordx4 v[202:203], v[196:199], off
	s_waitcnt lgkmcnt(5)
	v_mul_f32_e32 v172, 0xbfb8aa3b, v169
	v_mul_f32_e32 v173, v169, v169
	v_rcp_f32_e32 v173, v173
	v_mul_f32_e32 v176, v92, v172
	v_mul_f32_e32 v177, v93, v172
	v_mul_f32_e32 v178, v94, v172
	v_mul_f32_e32 v179, v95, v172
	v_mul_f32_e32 v180, v84, v172
	v_mul_f32_e32 v181, v85, v172
	v_mul_f32_e32 v182, v86, v172
	v_mul_f32_e32 v183, v87, v172
	v_exp_f32_e32 v176, v176
	v_exp_f32_e32 v177, v177
	v_exp_f32_e32 v178, v178
	v_exp_f32_e32 v179, v179
	v_exp_f32_e32 v180, v180
	v_exp_f32_e32 v181, v181
	v_exp_f32_e32 v182, v182
	v_exp_f32_e32 v183, v183
	v_mul_f32_e32 v184, v92, v88
	v_mul_f32_e32 v185, v93, v89
	v_mul_f32_e32 v186, v94, v90
	v_mul_f32_e32 v187, v95, v91
	v_mul_f32_e32 v188, v84, v80
	v_mul_f32_e32 v189, v85, v81
	v_mul_f32_e32 v190, v86, v82
	v_mul_f32_e32 v191, v87, v83
	v_fma_f32 v176, v176, v173, v173
	v_fma_f32 v177, v177, v173, v173
	v_fma_f32 v178, v178, v173, v173
	v_fma_f32 v179, v179, v173, v173
	v_fma_f32 v180, v180, v173, v173
	v_fma_f32 v181, v181, v173, v173
	v_fma_f32 v182, v182, v173, v173
	v_fma_f32 v183, v183, v173, v173
	v_rcp_f32_e32 v176, v176
	v_rcp_f32_e32 v177, v177
	v_rcp_f32_e32 v178, v178
	v_rcp_f32_e32 v179, v179
	v_rcp_f32_e32 v180, v180
	v_rcp_f32_e32 v181, v181
	v_rcp_f32_e32 v182, v182
	v_rcp_f32_e32 v183, v183
	v_add_u32_e32 v200, 32, v159
	v_mad_i64_i32 v[200:201], s[0:1], v200, s75, v[204:205]
	v_mul_f32_e32 v184, v184, v176
	v_mul_f32_e32 v185, v185, v177
	v_mul_f32_e32 v186, v186, v178
	v_mul_f32_e32 v187, v187, v179
	v_mul_f32_e32 v188, v188, v180
	v_mul_f32_e32 v189, v189, v181
	v_mul_f32_e32 v190, v190, v182
	v_mul_f32_e32 v191, v191, v183
	v_lshl_add_u64 v[200:201], v[200:201], 0, v[206:207]
	v_cvt_pk_bf16_f32 v192, v184, v185
	v_cvt_pk_bf16_f32 v193, v186, v187
	v_cvt_pk_bf16_f32 v194, v188, v189
	v_cvt_pk_bf16_f32 v195, v190, v191
	global_store_dwordx4 v[200:201], v[192:195], off
	s_waitcnt lgkmcnt(4)
; __device__ __forceinline__ unsigned cvt_pk_bf16(float lo, float hi) { unsigned r; asm volatile("v_cvt_pk_bf16_f32 %0, %1, %2" : "=v"(r) : "v"(lo), "v"(hi)); return r; }
;     __device__ __forceinline__ void operator()(const f32x4 (&acc)[2][2][4][2], const Unit& u, int wr, int wc, int fr, int fq) const {
;     ...
;             for (int m = 0; m < 4; ++m) { const int row = row0 + ai * HALF + m * 16; const float rs = rsv[ai][m];
;                 float o[8];
;                 const float rs2 = -1.4426950408889634f * rs, rq = rs * rs;
; #pragma unroll
;                 for (int n = 0; n < 2; ++n)
; #pragma unroll
;                     for (int i = 0; i < 4; ++i) { const float a = acc[ai][0][m][n][i], b = acc[ai][1][m][n][i];
;                         const float e = __builtin_amdgcn_exp2f(a * rs2); o[n * 4 + i] = (a * b) * (rq * __builtin_amdgcn_rcpf(1.0f + e)); }
;                 u32x4 w; w.x = cvt_pk_bf16(o[0], o[1]); w.y = cvt_pk_bf16(o[2], o[3]); w.z = cvt_pk_bf16(o[4], o[5]); w.w = cvt_pk_bf16(o[6], o[7]);
;                 *(u32x4*)(O + (size_t)row * ldc + col0) = w; }
	v_mul_f32_e32 v172, 0xbfb8aa3b, v170
	v_mul_f32_e32 v173, v170, v170
	v_rcp_f32_e32 v173, v173
	v_mul_f32_e32 v176, v76, v172
	v_mul_f32_e32 v177, v77, v172
	v_mul_f32_e32 v178, v78, v172
	v_mul_f32_e32 v179, v79, v172
	v_mul_f32_e32 v180, v68, v172
	v_mul_f32_e32 v181, v69, v172
	v_mul_f32_e32 v182, v70, v172
	v_mul_f32_e32 v183, v71, v172
	v_exp_f32_e32 v176, v176
	v_exp_f32_e32 v177, v177
	v_exp_f32_e32 v178, v178
	v_exp_f32_e32 v179, v179
	v_exp_f32_e32 v180, v180
	v_exp_f32_e32 v181, v181
	v_exp_f32_e32 v182, v182
	v_exp_f32_e32 v183, v183
	v_mul_f32_e32 v184, v76, v72
	v_mul_f32_e32 v185, v77, v73
	v_mul_f32_e32 v186, v78, v74
	v_mul_f32_e32 v187, v79, v75
	v_mul_f32_e32 v188, v68, v64
	v_mul_f32_e32 v189, v69, v65
	v_mul_f32_e32 v190, v70, v66
	v_mul_f32_e32 v191, v71, v67
	v_fma_f32 v176, v176, v173, v173
	v_fma_f32 v177, v177, v173, v173
	v_fma_f32 v178, v178, v173, v173
	v_fma_f32 v179, v179, v173, v173
	v_fma_f32 v180, v180, v173, v173
	v_fma_f32 v181, v181, v173, v173
	v_fma_f32 v182, v182, v173, v173
	v_fma_f32 v183, v183, v173, v173
	v_rcp_f32_e32 v176, v176
	v_rcp_f32_e32 v177, v177
	v_rcp_f32_e32 v178, v178
	v_rcp_f32_e32 v179, v179
	v_rcp_f32_e32 v180, v180
	v_rcp_f32_e32 v181, v181
	v_rcp_f32_e32 v182, v182
	v_rcp_f32_e32 v183, v183
	v_add_u32_e32 v202, 48, v159
	v_mad_i64_i32 v[202:203], s[0:1], v202, s75, v[204:205]
	v_mul_f32_e32 v184, v184, v176
	v_mul_f32_e32 v185, v185, v177
	v_mul_f32_e32 v186, v186, v178
	v_mul_f32_e32 v187, v187, v179
	v_mul_f32_e32 v188, v188, v180
	v_mul_f32_e32 v189, v189, v181
	v_mul_f32_e32 v190, v190, v182
	v_mul_f32_e32 v191, v191, v183
	v_lshl_add_u64 v[202:203], v[202:203], 0, v[206:207]
	v_cvt_pk_bf16_f32 v196, v184, v185
	v_cvt_pk_bf16_f32 v197, v186, v187
	v_cvt_pk_bf16_f32 v198, v188, v189
	v_cvt_pk_bf16_f32 v199, v190, v191
	global_store_dwordx4 v[202:203], v[196:199], off
	s_waitcnt lgkmcnt(3)
	v_mul_f32_e32 v172, 0xbfb8aa3b, v163
	v_mul_f32_e32 v173, v163, v163
	v_rcp_f32_e32 v173, v173
	v_mul_f32_e32 v176, v60, v172
	v_mul_f32_e32 v177, v61, v172
	v_mul_f32_e32 v178, v62, v172
	v_mul_f32_e32 v179, v63, v172
	v_mul_f32_e32 v180, v52, v172
	v_mul_f32_e32 v181, v53, v172
	v_mul_f32_e32 v182, v54, v172
	v_mul_f32_e32 v183, v55, v172
	v_exp_f32_e32 v176, v176
	v_exp_f32_e32 v177, v177
	v_exp_f32_e32 v178, v178
	v_exp_f32_e32 v179, v179
	v_exp_f32_e32 v180, v180
	v_exp_f32_e32 v181, v181
	v_exp_f32_e32 v182, v182
	v_exp_f32_e32 v183, v183
	v_mul_f32_e32 v184, v60, v56
	v_mul_f32_e32 v185, v61, v57
	v_mul_f32_e32 v186, v62, v58
	v_mul_f32_e32 v187, v63, v59
	v_mul_f32_e32 v188, v52, v48
	v_mul_f32_e32 v189, v53, v49
	v_mul_f32_e32 v190, v54, v50
	v_mul_f32_e32 v191, v55, v51
	v_fma_f32 v176, v176, v173, v173
	v_fma_f32 v177, v177, v173, v173
	v_fma_f32 v178, v178, v173, v173
	v_fma_f32 v179, v179, v173, v173
	v_fma_f32 v180, v180, v173, v173
	v_fma_f32 v181, v181, v173, v173
	v_fma_f32 v182, v182, v173, v173
	v_fma_f32 v183, v183, v173, v173
	v_rcp_f32_e32 v176, v176
	v_rcp_f32_e32 v177, v177
	v_rcp_f32_e32 v178, v178
	v_rcp_f32_e32 v179, v179
	v_rcp_f32_e32 v180, v180
	v_rcp_f32_e32 v181, v181
	v_rcp_f32_e32 v182, v182
	v_rcp_f32_e32 v183, v183
	v_add_u32_e32 v200, 128, v159
	v_mad_i64_i32 v[200:201], s[0:1], v200, s75, v[204:205]
	v_mul_f32_e32 v184, v184, v176
	v_mul_f32_e32 v185, v185, v177
	v_mul_f32_e32 v186, v186, v178
	v_mul_f32_e32 v187, v187, v179
	v_mul_f32_e32 v188, v188, v180
	v_mul_f32_e32 v189, v189, v181
	v_mul_f32_e32 v190, v190, v182
	v_mul_f32_e32 v191, v191, v183
	v_lshl_add_u64 v[200:201], v[200:201], 0, v[206:207]
	v_cvt_pk_bf16_f32 v192, v184, v185
	v_cvt_pk_bf16_f32 v193, v186, v187
	v_cvt_pk_bf16_f32 v194, v188, v189
	v_cvt_pk_bf16_f32 v195, v190, v191
	global_store_dwordx4 v[200:201], v[192:195], off
	s_waitcnt lgkmcnt(2)
	v_mul_f32_e32 v172, 0xbfb8aa3b, v162
	v_mul_f32_e32 v173, v162, v162
	v_rcp_f32_e32 v173, v173
	v_mul_f32_e32 v176, v44, v172
	v_mul_f32_e32 v177, v45, v172
	v_mul_f32_e32 v178, v46, v172
	v_mul_f32_e32 v179, v47, v172
	v_mul_f32_e32 v180, v36, v172
	v_mul_f32_e32 v181, v37, v172
	v_mul_f32_e32 v182, v38, v172
	v_mul_f32_e32 v183, v39, v172
	v_exp_f32_e32 v176, v176
	v_exp_f32_e32 v177, v177
	v_exp_f32_e32 v178, v178
	v_exp_f32_e32 v179, v179
	v_exp_f32_e32 v180, v180
	v_exp_f32_e32 v181, v181
	v_exp_f32_e32 v182, v182
	v_exp_f32_e32 v183, v183
	v_mul_f32_e32 v184, v44, v40
	v_mul_f32_e32 v185, v45, v41
	v_mul_f32_e32 v186, v46, v42
	v_mul_f32_e32 v187, v47, v43
	v_mul_f32_e32 v188, v36, v32
	v_mul_f32_e32 v189, v37, v33
	v_mul_f32_e32 v190, v38, v34
	v_mul_f32_e32 v191, v39, v35
	v_fma_f32 v176, v176, v173, v173
	v_fma_f32 v177, v177, v173, v173
	v_fma_f32 v178, v178, v173, v173
	v_fma_f32 v179, v179, v173, v173
	v_fma_f32 v180, v180, v173, v173
	v_fma_f32 v181, v181, v173, v173
	v_fma_f32 v182, v182, v173, v173
	v_fma_f32 v183, v183, v173, v173
	v_rcp_f32_e32 v176, v176
	v_rcp_f32_e32 v177, v177
	v_rcp_f32_e32 v178, v178
	v_rcp_f32_e32 v179, v179
	v_rcp_f32_e32 v180, v180
	v_rcp_f32_e32 v181, v181
	v_rcp_f32_e32 v182, v182
	v_rcp_f32_e32 v183, v183
	v_add_u32_e32 v202, 144, v159
	v_mad_i64_i32 v[202:203], s[0:1], v202, s75, v[204:205]
	v_mul_f32_e32 v184, v184, v176
	v_mul_f32_e32 v185, v185, v177
	v_mul_f32_e32 v186, v186, v178
	v_mul_f32_e32 v187, v187, v179
	v_mul_f32_e32 v188, v188, v180
	v_mul_f32_e32 v189, v189, v181
	v_mul_f32_e32 v190, v190, v182
	v_mul_f32_e32 v191, v191, v183
	v_lshl_add_u64 v[202:203], v[202:203], 0, v[206:207]
	v_cvt_pk_bf16_f32 v196, v184, v185
	v_cvt_pk_bf16_f32 v197, v186, v187
	v_cvt_pk_bf16_f32 v198, v188, v189
	v_cvt_pk_bf16_f32 v199, v190, v191
	global_store_dwordx4 v[202:203], v[196:199], off
	s_waitcnt lgkmcnt(1)
; __device__ __forceinline__ unsigned cvt_pk_bf16(float lo, float hi) { unsigned r; asm volatile("v_cvt_pk_bf16_f32 %0, %1, %2" : "=v"(r) : "v"(lo), "v"(hi)); return r; }
;     __device__ __forceinline__ void operator()(const f32x4 (&acc)[2][2][4][2], const Unit& u, int wr, int wc, int fr, int fq) const {
;     ...
;             for (int m = 0; m < 4; ++m) { const int row = row0 + ai * HALF + m * 16; const float rs = rsv[ai][m];
;                 float o[8];
;                 const float rs2 = -1.4426950408889634f * rs, rq = rs * rs;
; #pragma unroll
;                 for (int n = 0; n < 2; ++n)
; #pragma unroll
;                     for (int i = 0; i < 4; ++i) { const float a = acc[ai][0][m][n][i], b = acc[ai][1][m][n][i];
;                         const float e = __builtin_amdgcn_exp2f(a * rs2); o[n * 4 + i] = (a * b) * (rq * __builtin_amdgcn_rcpf(1.0f + e)); }
;                 u32x4 w; w.x = cvt_pk_bf16(o[0], o[1]); w.y = cvt_pk_bf16(o[2], o[3]); w.z = cvt_pk_bf16(o[4], o[5]); w.w = cvt_pk_bf16(o[6], o[7]);
;                 *(u32x4*)(O + (size_t)row * ldc + col0) = w; }
	v_mul_f32_e32 v172, 0xbfb8aa3b, v161
	v_mul_f32_e32 v173, v161, v161
	v_rcp_f32_e32 v173, v173
	v_mul_f32_e32 v176, v28, v172
	v_mul_f32_e32 v177, v29, v172
	v_mul_f32_e32 v178, v30, v172
	v_mul_f32_e32 v179, v31, v172
	v_mul_f32_e32 v180, v20, v172
	v_mul_f32_e32 v181, v21, v172
	v_mul_f32_e32 v182, v22, v172
	v_mul_f32_e32 v183, v23, v172
	v_exp_f32_e32 v176, v176
	v_exp_f32_e32 v177, v177
	v_exp_f32_e32 v178, v178
	v_exp_f32_e32 v179, v179
	v_exp_f32_e32 v180, v180
	v_exp_f32_e32 v181, v181
	v_exp_f32_e32 v182, v182
	v_exp_f32_e32 v183, v183
	v_mul_f32_e32 v184, v28, v24
	v_mul_f32_e32 v185, v29, v25
	v_mul_f32_e32 v186, v30, v26
	v_mul_f32_e32 v187, v31, v27
	v_mul_f32_e32 v188, v20, v16
	v_mul_f32_e32 v189, v21, v17
	v_mul_f32_e32 v190, v22, v18
	v_mul_f32_e32 v191, v23, v19
	v_fma_f32 v176, v176, v173, v173
	v_fma_f32 v177, v177, v173, v173
	v_fma_f32 v178, v178, v173, v173
	v_fma_f32 v179, v179, v173, v173
	v_fma_f32 v180, v180, v173, v173
	v_fma_f32 v181, v181, v173, v173
	v_fma_f32 v182, v182, v173, v173
	v_fma_f32 v183, v183, v173, v173
	v_rcp_f32_e32 v176, v176
	v_rcp_f32_e32 v177, v177
	v_rcp_f32_e32 v178, v178
	v_rcp_f32_e32 v179, v179
	v_rcp_f32_e32 v180, v180
	v_rcp_f32_e32 v181, v181
	v_rcp_f32_e32 v182, v182
	v_rcp_f32_e32 v183, v183
	v_add_u32_e32 v200, 160, v159
	v_mad_i64_i32 v[200:201], s[0:1], v200, s75, v[204:205]
	v_mul_f32_e32 v184, v184, v176
	v_mul_f32_e32 v185, v185, v177
	v_mul_f32_e32 v186, v186, v178
	v_mul_f32_e32 v187, v187, v179
	v_mul_f32_e32 v188, v188, v180
	v_mul_f32_e32 v189, v189, v181
	v_mul_f32_e32 v190, v190, v182
	v_mul_f32_e32 v191, v191, v183
	v_lshl_add_u64 v[200:201], v[200:201], 0, v[206:207]
	v_cvt_pk_bf16_f32 v192, v184, v185
	v_cvt_pk_bf16_f32 v193, v186, v187
	v_cvt_pk_bf16_f32 v194, v188, v189
	v_cvt_pk_bf16_f32 v195, v190, v191
	global_store_dwordx4 v[200:201], v[192:195], off
	s_waitcnt lgkmcnt(0)
	v_mul_f32_e32 v172, 0xbfb8aa3b, v232
	v_mul_f32_e32 v173, v232, v232
	v_rcp_f32_e32 v173, v173
	v_mul_f32_e32 v176, v12, v172
	v_mul_f32_e32 v177, v13, v172
	v_mul_f32_e32 v178, v14, v172
	v_mul_f32_e32 v179, v15, v172
	v_mul_f32_e32 v180, v4, v172
	v_mul_f32_e32 v181, v5, v172
	v_mul_f32_e32 v182, v6, v172
	v_mul_f32_e32 v183, v7, v172
	v_exp_f32_e32 v176, v176
	v_exp_f32_e32 v177, v177
	v_exp_f32_e32 v178, v178
	v_exp_f32_e32 v179, v179
	v_exp_f32_e32 v180, v180
	v_exp_f32_e32 v181, v181
	v_exp_f32_e32 v182, v182
	v_exp_f32_e32 v183, v183
	v_mul_f32_e32 v184, v12, v8
	v_mul_f32_e32 v185, v13, v9
	v_mul_f32_e32 v186, v14, v10
	v_mul_f32_e32 v187, v15, v11
	v_mul_f32_e32 v188, v4, v0
	v_mul_f32_e32 v189, v5, v1
	v_mul_f32_e32 v190, v6, v2
	v_mul_f32_e32 v191, v7, v3
	v_fma_f32 v176, v176, v173, v173
	v_fma_f32 v177, v177, v173, v173
	v_fma_f32 v178, v178, v173, v173
	v_fma_f32 v179, v179, v173, v173
	v_fma_f32 v180, v180, v173, v173
	v_fma_f32 v181, v181, v173, v173
	v_fma_f32 v182, v182, v173, v173
	v_fma_f32 v183, v183, v173, v173
	v_rcp_f32_e32 v176, v176
	v_rcp_f32_e32 v177, v177
	v_rcp_f32_e32 v178, v178
	v_rcp_f32_e32 v179, v179
	v_rcp_f32_e32 v180, v180
	v_rcp_f32_e32 v181, v181
	v_rcp_f32_e32 v182, v182
	v_rcp_f32_e32 v183, v183
	v_add_u32_e32 v202, 176, v159
	v_mad_i64_i32 v[202:203], s[0:1], v202, s75, v[204:205]
	v_mul_f32_e32 v184, v184, v176
	v_mul_f32_e32 v185, v185, v177
	v_mul_f32_e32 v186, v186, v178
	v_mul_f32_e32 v187, v187, v179
	v_mul_f32_e32 v188, v188, v180
	v_mul_f32_e32 v189, v189, v181
	v_mul_f32_e32 v190, v190, v182
	v_mul_f32_e32 v191, v191, v183
	v_lshl_add_u64 v[202:203], v[202:203], 0, v[206:207]
	v_cvt_pk_bf16_f32 v196, v184, v185
	v_cvt_pk_bf16_f32 v197, v186, v187
	v_cvt_pk_bf16_f32 v198, v188, v189
	v_cvt_pk_bf16_f32 v199, v190, v191
	global_store_dwordx4 v[202:203], v[196:199], off
	s_mov_b64 s[0:1], -1
	s_cbranch_vccnz .LBB0_1192
	s_andn2_b64 vcc, exec, s[20:21]
	s_cbranch_vccnz .LBB0_1191
	s_barrier
	s_branch .LBB0_1191

; __device__ __forceinline__ void wave_row_rs(const float* SS, int base, int fr, int fq, float (&rs)[2][4]) {
;     const int L = fq * 16 + fr; float mine[2]; f32x4 p[2][4];
; #pragma unroll
;     for (int ai = 0; ai < 2; ++ai) { const f32x4* q = (const f32x4*)(SS + (size_t)(base + ai * HALF + L) * 16);
; #pragma unroll
;         for (int j = 0; j < 4; ++j) p[ai][j] = q[j]; }
; #pragma unroll
;     for (int ai = 0; ai < 2; ++ai) { const f32x4 a = p[ai][0], b = p[ai][1], c = p[ai][2], d = p[ai][3];
;         const float s = ((a[0] + a[1]) + (a[2] + a[3])) + ((b[0] + b[1]) + (b[2] + b[3])) + ((c[0] + c[1]) + (c[2] + c[3])) + ((d[0] + d[1]) + (d[2] + d[3]));
;         mine[ai] = 1.0f / sqrtf(s * (1.0f / 1024.0f) + 1e-6f); }
; #pragma unroll
;     for (int ai = 0; ai < 2; ++ai)
; #pragma unroll
;         for (int m = 0; m < 4; ++m) rs[ai][m] = __int_as_float(__builtin_amdgcn_ds_bpermute((m * 16 + fr) * 4, __float_as_int(mine[ai])));
; }
;     __device__ __forceinline__ void operator()(const f32x4 (&acc)[2][2][4][2], const Unit& u, int wr, int wc, int fr, int fq) const {
;         const int row0 = u.pm * BM + wr * 64 + fr, col0 = u.pn * HALF + wc * 32 + 8 * fq;
;         float rsv[2][4]; wave_row_rs(SS, u.pm * BM + wr * 64, fr, fq, rsv);
.LBB0_3056:
	s_lshl_b32 s0, s8, 8
	s_add_i32 s0, s0, s42
	v_or_b32_e32 v144, s0, v149
	v_ashrrev_i32_e32 v145, 31, v144
	v_lshlrev_b64 v[160:161], 6, v[144:145]
	v_lshl_add_u64 v[172:173], s[14:15], 0, v[160:161]
	v_add_u32_e32 v144, 0x80, v144
	global_load_dwordx4 v[160:163], v[172:173], off
	global_load_dwordx4 v[164:167], v[172:173], off offset:16
	global_load_dwordx4 v[168:171], v[172:173], off offset:32
	s_nop 0
	global_load_dwordx4 v[172:175], v[172:173], off offset:48
	v_ashrrev_i32_e32 v145, 31, v144
	v_lshlrev_b64 v[144:145], 6, v[144:145]
	v_lshl_add_u64 v[144:145], s[14:15], 0, v[144:145]
	global_load_dwordx4 v[176:179], v[144:145], off
	global_load_dwordx4 v[180:183], v[144:145], off offset:16
	global_load_dwordx4 v[184:187], v[144:145], off offset:32
	global_load_dwordx4 v[188:191], v[144:145], off offset:48
	v_lshl_or_b32 v144, s9, 7, v153
	v_or_b32_e32 v159, s0, v146
	s_waitcnt vmcnt(0)
	v_mov_b32_e32 v192, v161
	v_mov_b32_e32 v193, v162
	v_mov_b32_e32 v161, v163
	v_mov_b32_e32 v162, v165
	v_mov_b32_e32 v163, v166
	v_mov_b32_e32 v165, v167
	v_add_f32_e32 v166, v168, v169
	v_add_f32_e32 v168, v170, v171
	v_mov_b32_e32 v167, v174
	v_mov_b32_e32 v169, v175
	v_pk_add_f32 v[160:161], v[192:193], v[160:161]
	v_pk_add_f32 v[162:163], v[162:163], v[164:165]
	v_pk_add_f32 v[164:165], v[166:167], v[168:169]
	v_mov_b32_e32 v166, v177
	v_mov_b32_e32 v167, v178
	v_mov_b32_e32 v177, v179
	v_mov_b32_e32 v168, v181
	v_mov_b32_e32 v169, v182
	v_mov_b32_e32 v181, v183
	v_pk_add_f32 v[160:161], v[160:161], v[160:161] op_sel:[0,1] op_sel_hi:[1,0]
	v_pk_add_f32 v[162:163], v[162:163], v[162:163] op_sel:[0,1] op_sel_hi:[1,0]
	v_pk_add_f32 v[166:167], v[166:167], v[176:177]
	v_pk_add_f32 v[168:169], v[168:169], v[180:181]
	v_mov_b32_e32 v161, v172
	v_mov_b32_e32 v163, v173
	v_pk_add_f32 v[166:167], v[166:167], v[166:167] op_sel:[0,1] op_sel_hi:[1,0]
	v_pk_add_f32 v[168:169], v[168:169], v[168:169] op_sel:[0,1] op_sel_hi:[1,0]
	v_pk_add_f32 v[160:161], v[160:161], v[162:163]
	v_add_f32_e32 v170, v184, v185
	v_add_f32_e32 v174, v186, v187
	v_mov_b32_e32 v171, v190
	v_mov_b32_e32 v175, v191
	v_mov_b32_e32 v167, v188
	v_mov_b32_e32 v169, v189
	v_pk_add_f32 v[160:161], v[160:161], v[164:165]
	v_pk_add_f32 v[170:171], v[170:171], v[174:175]
	v_pk_add_f32 v[162:163], v[166:167], v[168:169]
	v_add_f32_e32 v145, v160, v161
	v_pk_add_f32 v[160:161], v[162:163], v[170:171]
	v_fmamk_f32 v145, v145, 0x3a800000, v157
	v_add_f32_e32 v160, v160, v161
	v_mul_f32_e32 v161, 0x4f800000, v145
	v_cmp_gt_f32_e32 vcc, s47, v145
	v_fmamk_f32 v160, v160, 0x3a800000, v157
	v_cmp_gt_f32_e64 s[8:9], s47, v160
	v_cndmask_b32_e32 v145, v145, v161, vcc
	v_mul_f32_e32 v161, 0x4f800000, v160
	v_sqrt_f32_e32 v162, v145
	v_cndmask_b32_e64 v160, v160, v161, s[8:9]
	v_sqrt_f32_e32 v161, v160
	v_add_u32_e32 v163, -1, v162
	v_add_u32_e32 v164, 1, v162
	v_fma_f32 v165, -v163, v162, v145
	v_fma_f32 v166, -v164, v162, v145
	v_add_u32_e32 v167, -1, v161
	v_cmp_ge_f32_e64 s[10:11], 0, v165
	v_add_u32_e32 v168, 1, v161
	v_fma_f32 v165, -v168, v161, v160
	v_cndmask_b32_e64 v162, v162, v163, s[10:11]
	v_fma_f32 v163, -v167, v161, v160
	v_cmp_lt_f32_e64 s[10:11], 0, v166
	s_nop 1
	v_cndmask_b32_e64 v162, v162, v164, s[10:11]
	v_cmp_ge_f32_e64 s[10:11], 0, v163
	v_mul_f32_e32 v163, 0x37800000, v162
	v_cndmask_b32_e32 v162, v162, v163, vcc
	v_cndmask_b32_e64 v161, v161, v167, s[10:11]
	v_cmp_lt_f32_e64 s[10:11], 0, v165
	v_cmp_class_f32_e32 vcc, v145, v158
	s_nop 0
	v_cndmask_b32_e64 v161, v161, v168, s[10:11]
	v_mul_f32_e32 v163, 0x37800000, v161
	v_cndmask_b32_e32 v145, v162, v145, vcc
	v_cndmask_b32_e64 v161, v161, v163, s[8:9]
	v_div_scale_f32 v162, s[0:1], v145, v145, 1.0
	v_cmp_class_f32_e64 s[8:9], v160, v158
	v_div_scale_f32 v163, vcc, 1.0, v145, 1.0
	s_nop 0
	v_cndmask_b32_e64 v160, v161, v160, s[8:9]
	v_rcp_f32_e32 v161, v162
	v_div_scale_f32 v164, s[0:1], v160, v160, 1.0
	v_rcp_f32_e32 v165, v164
	v_fma_f32 v167, -v162, v161, 1.0
	v_fmac_f32_e32 v161, v167, v161
	v_mul_f32_e32 v168, v163, v161
	v_fma_f32 v167, -v164, v165, 1.0
	v_fmac_f32_e32 v165, v167, v165
	v_fma_f32 v167, -v162, v168, v163
	v_div_scale_f32 v166, s[8:9], 1.0, v160, 1.0
	v_fmac_f32_e32 v168, v167, v161
	v_mul_f32_e32 v169, v166, v165
	v_fma_f32 v162, -v162, v168, v163
	v_fma_f32 v167, -v164, v169, v166
	v_div_fmas_f32 v161, v162, v161, v168
	v_fmac_f32_e32 v169, v167, v165
	v_div_fixup_f32 v145, v161, v145, 1.0
	v_fma_f32 v162, -v164, v169, v166
	ds_bpermute_b32 v164, v147, v145
	s_mov_b64 vcc, s[8:9]
	v_div_fmas_f32 v161, v162, v165, v169
	ds_bpermute_b32 v168, v150, v145
	ds_bpermute_b32 v169, v151, v145
	ds_bpermute_b32 v170, v152, v145
	v_div_fixup_f32 v160, v161, v160, 1.0
	v_ashrrev_i32_e32 v145, 31, v144
	ds_bpermute_b32 v163, v147, v160
	ds_bpermute_b32 v162, v150, v160
	ds_bpermute_b32 v161, v151, v160
	ds_bpermute_b32 v232, v152, v160
	v_mov_b64_e32 v[204:205], s[16:17]
	v_lshlrev_b64 v[206:207], 1, v[144:145]
	s_andn2_b64 vcc, exec, s[6:7]
	s_waitcnt lgkmcnt(7)
; __device__ __forceinline__ unsigned cvt_pk_bf16(float lo, float hi) { unsigned r; asm volatile("v_cvt_pk_bf16_f32 %0, %1, %2" : "=v"(r) : "v"(lo), "v"(hi)); return r; }
;     __device__ __forceinline__ void operator()(const f32x4 (&acc)[2][2][4][2], const Unit& u, int wr, int wc, int fr, int fq) const {
;     ...
;             for (int m = 0; m < 4; ++m) { const int row = row0 + ai * HALF + m * 16; const float rs = rsv[ai][m];
;                 float o[8];
;                 const float rs2 = -1.4426950408889634f * rs, rq = rs * rs;
; #pragma unroll
;                 for (int n = 0; n < 2; ++n)
; #pragma unroll
;                     for (int i = 0; i < 4; ++i) { const float a = acc[ai][0][m][n][i], b = acc[ai][1][m][n][i];
;                         const float e = __builtin_amdgcn_exp2f(a * rs2); o[n * 4 + i] = (a * b) * (rq * __builtin_amdgcn_rcpf(1.0f + e)); }
;                 u32x4 w; w.x = cvt_pk_bf16(o[0], o[1]); w.y = cvt_pk_bf16(o[2], o[3]); w.z = cvt_pk_bf16(o[4], o[5]); w.w = cvt_pk_bf16(o[6], o[7]);
;                 *(u32x4*)(O + (size_t)row * ldc + col0) = w; }
	v_mul_f32_e32 v172, 0xbfb8aa3b, v164
	v_mul_f32_e32 v173, v164, v164
	v_rcp_f32_e32 v173, v173
	v_mul_f32_e32 v176, v124, v172
	v_mul_f32_e32 v177, v125, v172
	v_mul_f32_e32 v178, v126, v172
	v_mul_f32_e32 v179, v127, v172
	v_mul_f32_e32 v180, v116, v172
	v_mul_f32_e32 v181, v117, v172
	v_mul_f32_e32 v182, v118, v172
	v_mul_f32_e32 v183, v119, v172
	v_exp_f32_e32 v176, v176
	v_exp_f32_e32 v177, v177
	v_exp_f32_e32 v178, v178
	v_exp_f32_e32 v179, v179
	v_exp_f32_e32 v180, v180
	v_exp_f32_e32 v181, v181
	v_exp_f32_e32 v182, v182
	v_exp_f32_e32 v183, v183
	v_mul_f32_e32 v184, v124, v120
	v_mul_f32_e32 v185, v125, v121
	v_mul_f32_e32 v186, v126, v122
	v_mul_f32_e32 v187, v127, v123
	v_mul_f32_e32 v188, v116, v112
	v_mul_f32_e32 v189, v117, v113
	v_mul_f32_e32 v190, v118, v114
	v_mul_f32_e32 v191, v119, v115
	v_fma_f32 v176, v176, v173, v173
	v_fma_f32 v177, v177, v173, v173
	v_fma_f32 v178, v178, v173, v173
	v_fma_f32 v179, v179, v173, v173
	v_fma_f32 v180, v180, v173, v173
	v_fma_f32 v181, v181, v173, v173
	v_fma_f32 v182, v182, v173, v173
	v_fma_f32 v183, v183, v173, v173
	v_rcp_f32_e32 v176, v176
	v_rcp_f32_e32 v177, v177
	v_rcp_f32_e32 v178, v178
	v_rcp_f32_e32 v179, v179
	v_rcp_f32_e32 v180, v180
	v_rcp_f32_e32 v181, v181
	v_rcp_f32_e32 v182, v182
	v_rcp_f32_e32 v183, v183
	v_add_u32_e32 v200, 0, v159
	v_mad_i64_i32 v[200:201], s[0:1], v200, s48, v[204:205]
	v_mul_f32_e32 v184, v184, v176
	v_mul_f32_e32 v185, v185, v177
	v_mul_f32_e32 v186, v186, v178
	v_mul_f32_e32 v187, v187, v179
	v_mul_f32_e32 v188, v188, v180
	v_mul_f32_e32 v189, v189, v181
	v_mul_f32_e32 v190, v190, v182
	v_mul_f32_e32 v191, v191, v183
	v_lshl_add_u64 v[200:201], v[200:201], 0, v[206:207]
	v_cvt_pk_bf16_f32 v192, v184, v185
	v_cvt_pk_bf16_f32 v193, v186, v187
	v_cvt_pk_bf16_f32 v194, v188, v189
	v_cvt_pk_bf16_f32 v195, v190, v191
	global_store_dwordx4 v[200:201], v[192:195], off
	s_waitcnt lgkmcnt(6)
	v_mul_f32_e32 v172, 0xbfb8aa3b, v168
	v_mul_f32_e32 v173, v168, v168
	v_rcp_f32_e32 v173, v173
	v_mul_f32_e32 v176, v108, v172
	v_mul_f32_e32 v177, v109, v172
	v_mul_f32_e32 v178, v110, v172
	v_mul_f32_e32 v179, v111, v172
	v_mul_f32_e32 v180, v100, v172
	v_mul_f32_e32 v181, v101, v172
	v_mul_f32_e32 v182, v102, v172
	v_mul_f32_e32 v183, v103, v172
	v_exp_f32_e32 v176, v176
	v_exp_f32_e32 v177, v177
	v_exp_f32_e32 v178, v178
	v_exp_f32_e32 v179, v179
	v_exp_f32_e32 v180, v180
	v_exp_f32_e32 v181, v181
	v_exp_f32_e32 v182, v182
	v_exp_f32_e32 v183, v183
	v_mul_f32_e32 v184, v108, v104
	v_mul_f32_e32 v185, v109, v105
	v_mul_f32_e32 v186, v110, v106
	v_mul_f32_e32 v187, v111, v107
	v_mul_f32_e32 v188, v100, v96
	v_mul_f32_e32 v189, v101, v97
	v_mul_f32_e32 v190, v102, v98
	v_mul_f32_e32 v191, v103, v99
	v_fma_f32 v176, v176, v173, v173
	v_fma_f32 v177, v177, v173, v173
	v_fma_f32 v178, v178, v173, v173
	v_fma_f32 v179, v179, v173, v173
	v_fma_f32 v180, v180, v173, v173
	v_fma_f32 v181, v181, v173, v173
	v_fma_f32 v182, v182, v173, v173
	v_fma_f32 v183, v183, v173, v173
	v_rcp_f32_e32 v176, v176
	v_rcp_f32_e32 v177, v177
	v_rcp_f32_e32 v178, v178
	v_rcp_f32_e32 v179, v179
	v_rcp_f32_e32 v180, v180
	v_rcp_f32_e32 v181, v181
	v_rcp_f32_e32 v182, v182
	v_rcp_f32_e32 v183, v183
	v_add_u32_e32 v202, 16, v159
	v_mad_i64_i32 v[202:203], s[0:1], v202, s48, v[204:205]
	v_mul_f32_e32 v184, v184, v176
	v_mul_f32_e32 v185, v185, v177
	v_mul_f32_e32 v186, v186, v178
	v_mul_f32_e32 v187, v187, v179
	v_mul_f32_e32 v188, v188, v180
	v_mul_f32_e32 v189, v189, v181
	v_mul_f32_e32 v190, v190, v182
	v_mul_f32_e32 v191, v191, v183
	v_lshl_add_u64 v[202:203], v[202:203], 0, v[206:207]
	v_cvt_pk_bf16_f32 v196, v184, v185
	v_cvt_pk_bf16_f32 v197, v186, v187
	v_cvt_pk_bf16_f32 v198, v188, v189
	v_cvt_pk_bf16_f32 v199, v190, v191
	global_store_dwordx4 v[202:203], v[196:199], off
	s_waitcnt lgkmcnt(5)
	v_mul_f32_e32 v172, 0xbfb8aa3b, v169
	v_mul_f32_e32 v173, v169, v169
	v_rcp_f32_e32 v173, v173
	v_mul_f32_e32 v176, v92, v172
	v_mul_f32_e32 v177, v93, v172
	v_mul_f32_e32 v178, v94, v172
	v_mul_f32_e32 v179, v95, v172
	v_mul_f32_e32 v180, v84, v172
	v_mul_f32_e32 v181, v85, v172
	v_mul_f32_e32 v182, v86, v172
	v_mul_f32_e32 v183, v87, v172
	v_exp_f32_e32 v176, v176
	v_exp_f32_e32 v177, v177
	v_exp_f32_e32 v178, v178
	v_exp_f32_e32 v179, v179
	v_exp_f32_e32 v180, v180
	v_exp_f32_e32 v181, v181
	v_exp_f32_e32 v182, v182
	v_exp_f32_e32 v183, v183
	v_mul_f32_e32 v184, v92, v88
	v_mul_f32_e32 v185, v93, v89
	v_mul_f32_e32 v186, v94, v90
	v_mul_f32_e32 v187, v95, v91
	v_mul_f32_e32 v188, v84, v80
	v_mul_f32_e32 v189, v85, v81
	v_mul_f32_e32 v190, v86, v82
	v_mul_f32_e32 v191, v87, v83
	v_fma_f32 v176, v176, v173, v173
	v_fma_f32 v177, v177, v173, v173
	v_fma_f32 v178, v178, v173, v173
	v_fma_f32 v179, v179, v173, v173
	v_fma_f32 v180, v180, v173, v173
	v_fma_f32 v181, v181, v173, v173
	v_fma_f32 v182, v182, v173, v173
	v_fma_f32 v183, v183, v173, v173
	v_rcp_f32_e32 v176, v176
	v_rcp_f32_e32 v177, v177
	v_rcp_f32_e32 v178, v178
	v_rcp_f32_e32 v179, v179
	v_rcp_f32_e32 v180, v180
	v_rcp_f32_e32 v181, v181
	v_rcp_f32_e32 v182, v182
	v_rcp_f32_e32 v183, v183
	v_add_u32_e32 v200, 32, v159
	v_mad_i64_i32 v[200:201], s[0:1], v200, s48, v[204:205]
	v_mul_f32_e32 v184, v184, v176
	v_mul_f32_e32 v185, v185, v177
	v_mul_f32_e32 v186, v186, v178
	v_mul_f32_e32 v187, v187, v179
	v_mul_f32_e32 v188, v188, v180
	v_mul_f32_e32 v189, v189, v181
	v_mul_f32_e32 v190, v190, v182
	v_mul_f32_e32 v191, v191, v183
	v_lshl_add_u64 v[200:201], v[200:201], 0, v[206:207]
	v_cvt_pk_bf16_f32 v192, v184, v185
	v_cvt_pk_bf16_f32 v193, v186, v187
	v_cvt_pk_bf16_f32 v194, v188, v189
	v_cvt_pk_bf16_f32 v195, v190, v191
	global_store_dwordx4 v[200:201], v[192:195], off
	s_waitcnt lgkmcnt(4)
; __device__ __forceinline__ unsigned cvt_pk_bf16(float lo, float hi) { unsigned r; asm volatile("v_cvt_pk_bf16_f32 %0, %1, %2" : "=v"(r) : "v"(lo), "v"(hi)); return r; }
;     __device__ __forceinline__ void operator()(const f32x4 (&acc)[2][2][4][2], const Unit& u, int wr, int wc, int fr, int fq) const {
;     ...
;             for (int m = 0; m < 4; ++m) { const int row = row0 + ai * HALF + m * 16; const float rs = rsv[ai][m];
;                 float o[8];
;                 const float rs2 = -1.4426950408889634f * rs, rq = rs * rs;
; #pragma unroll
;                 for (int n = 0; n < 2; ++n)
; #pragma unroll
;                     for (int i = 0; i < 4; ++i) { const float a = acc[ai][0][m][n][i], b = acc[ai][1][m][n][i];
;                         const float e = __builtin_amdgcn_exp2f(a * rs2); o[n * 4 + i] = (a * b) * (rq * __builtin_amdgcn_rcpf(1.0f + e)); }
;                 u32x4 w; w.x = cvt_pk_bf16(o[0], o[1]); w.y = cvt_pk_bf16(o[2], o[3]); w.z = cvt_pk_bf16(o[4], o[5]); w.w = cvt_pk_bf16(o[6], o[7]);
;                 *(u32x4*)(O + (size_t)row * ldc + col0) = w; }
	v_mul_f32_e32 v172, 0xbfb8aa3b, v170
	v_mul_f32_e32 v173, v170, v170
	v_rcp_f32_e32 v173, v173
	v_mul_f32_e32 v176, v76, v172
	v_mul_f32_e32 v177, v77, v172
	v_mul_f32_e32 v178, v78, v172
	v_mul_f32_e32 v179, v79, v172
	v_mul_f32_e32 v180, v68, v172
	v_mul_f32_e32 v181, v69, v172
	v_mul_f32_e32 v182, v70, v172
	v_mul_f32_e32 v183, v71, v172
	v_exp_f32_e32 v176, v176
	v_exp_f32_e32 v177, v177
	v_exp_f32_e32 v178, v178
	v_exp_f32_e32 v179, v179
	v_exp_f32_e32 v180, v180
	v_exp_f32_e32 v181, v181
	v_exp_f32_e32 v182, v182
	v_exp_f32_e32 v183, v183
	v_mul_f32_e32 v184, v76, v72
	v_mul_f32_e32 v185, v77, v73
	v_mul_f32_e32 v186, v78, v74
	v_mul_f32_e32 v187, v79, v75
	v_mul_f32_e32 v188, v68, v64
	v_mul_f32_e32 v189, v69, v65
	v_mul_f32_e32 v190, v70, v66
	v_mul_f32_e32 v191, v71, v67
	v_fma_f32 v176, v176, v173, v173
	v_fma_f32 v177, v177, v173, v173
	v_fma_f32 v178, v178, v173, v173
	v_fma_f32 v179, v179, v173, v173
	v_fma_f32 v180, v180, v173, v173
	v_fma_f32 v181, v181, v173, v173
	v_fma_f32 v182, v182, v173, v173
	v_fma_f32 v183, v183, v173, v173
	v_rcp_f32_e32 v176, v176
	v_rcp_f32_e32 v177, v177
	v_rcp_f32_e32 v178, v178
	v_rcp_f32_e32 v179, v179
	v_rcp_f32_e32 v180, v180
	v_rcp_f32_e32 v181, v181
	v_rcp_f32_e32 v182, v182
	v_rcp_f32_e32 v183, v183
	v_add_u32_e32 v202, 48, v159
	v_mad_i64_i32 v[202:203], s[0:1], v202, s48, v[204:205]
	v_mul_f32_e32 v184, v184, v176
	v_mul_f32_e32 v185, v185, v177
	v_mul_f32_e32 v186, v186, v178
	v_mul_f32_e32 v187, v187, v179
	v_mul_f32_e32 v188, v188, v180
	v_mul_f32_e32 v189, v189, v181
	v_mul_f32_e32 v190, v190, v182
	v_mul_f32_e32 v191, v191, v183
	v_lshl_add_u64 v[202:203], v[202:203], 0, v[206:207]
	v_cvt_pk_bf16_f32 v196, v184, v185
	v_cvt_pk_bf16_f32 v197, v186, v187
	v_cvt_pk_bf16_f32 v198, v188, v189
	v_cvt_pk_bf16_f32 v199, v190, v191
	global_store_dwordx4 v[202:203], v[196:199], off
	s_waitcnt lgkmcnt(3)
	v_mul_f32_e32 v172, 0xbfb8aa3b, v163
	v_mul_f32_e32 v173, v163, v163
	v_rcp_f32_e32 v173, v173
	v_mul_f32_e32 v176, v60, v172
	v_mul_f32_e32 v177, v61, v172
	v_mul_f32_e32 v178, v62, v172
	v_mul_f32_e32 v179, v63, v172
	v_mul_f32_e32 v180, v52, v172
	v_mul_f32_e32 v181, v53, v172
	v_mul_f32_e32 v182, v54, v172
	v_mul_f32_e32 v183, v55, v172
	v_exp_f32_e32 v176, v176
	v_exp_f32_e32 v177, v177
	v_exp_f32_e32 v178, v178
	v_exp_f32_e32 v179, v179
	v_exp_f32_e32 v180, v180
	v_exp_f32_e32 v181, v181
	v_exp_f32_e32 v182, v182
	v_exp_f32_e32 v183, v183
	v_mul_f32_e32 v184, v60, v56
	v_mul_f32_e32 v185, v61, v57
	v_mul_f32_e32 v186, v62, v58
	v_mul_f32_e32 v187, v63, v59
	v_mul_f32_e32 v188, v52, v48
	v_mul_f32_e32 v189, v53, v49
	v_mul_f32_e32 v190, v54, v50
	v_mul_f32_e32 v191, v55, v51
	v_fma_f32 v176, v176, v173, v173
	v_fma_f32 v177, v177, v173, v173
	v_fma_f32 v178, v178, v173, v173
	v_fma_f32 v179, v179, v173, v173
	v_fma_f32 v180, v180, v173, v173
	v_fma_f32 v181, v181, v173, v173
	v_fma_f32 v182, v182, v173, v173
	v_fma_f32 v183, v183, v173, v173
	v_rcp_f32_e32 v176, v176
	v_rcp_f32_e32 v177, v177
	v_rcp_f32_e32 v178, v178
	v_rcp_f32_e32 v179, v179
	v_rcp_f32_e32 v180, v180
	v_rcp_f32_e32 v181, v181
	v_rcp_f32_e32 v182, v182
	v_rcp_f32_e32 v183, v183
	v_add_u32_e32 v200, 128, v159
	v_mad_i64_i32 v[200:201], s[0:1], v200, s48, v[204:205]
	v_mul_f32_e32 v184, v184, v176
	v_mul_f32_e32 v185, v185, v177
	v_mul_f32_e32 v186, v186, v178
	v_mul_f32_e32 v187, v187, v179
	v_mul_f32_e32 v188, v188, v180
	v_mul_f32_e32 v189, v189, v181
	v_mul_f32_e32 v190, v190, v182
	v_mul_f32_e32 v191, v191, v183
	v_lshl_add_u64 v[200:201], v[200:201], 0, v[206:207]
	v_cvt_pk_bf16_f32 v192, v184, v185
	v_cvt_pk_bf16_f32 v193, v186, v187
	v_cvt_pk_bf16_f32 v194, v188, v189
	v_cvt_pk_bf16_f32 v195, v190, v191
	global_store_dwordx4 v[200:201], v[192:195], off
	s_waitcnt lgkmcnt(2)
	v_mul_f32_e32 v172, 0xbfb8aa3b, v162
	v_mul_f32_e32 v173, v162, v162
	v_rcp_f32_e32 v173, v173
	v_mul_f32_e32 v176, v44, v172
	v_mul_f32_e32 v177, v45, v172
	v_mul_f32_e32 v178, v46, v172
	v_mul_f32_e32 v179, v47, v172
	v_mul_f32_e32 v180, v36, v172
	v_mul_f32_e32 v181, v37, v172
	v_mul_f32_e32 v182, v38, v172
	v_mul_f32_e32 v183, v39, v172
	v_exp_f32_e32 v176, v176
	v_exp_f32_e32 v177, v177
	v_exp_f32_e32 v178, v178
	v_exp_f32_e32 v179, v179
	v_exp_f32_e32 v180, v180
	v_exp_f32_e32 v181, v181
	v_exp_f32_e32 v182, v182
	v_exp_f32_e32 v183, v183
	v_mul_f32_e32 v184, v44, v40
	v_mul_f32_e32 v185, v45, v41
	v_mul_f32_e32 v186, v46, v42
	v_mul_f32_e32 v187, v47, v43
	v_mul_f32_e32 v188, v36, v32
	v_mul_f32_e32 v189, v37, v33
	v_mul_f32_e32 v190, v38, v34
	v_mul_f32_e32 v191, v39, v35
	v_fma_f32 v176, v176, v173, v173
	v_fma_f32 v177, v177, v173, v173
	v_fma_f32 v178, v178, v173, v173
	v_fma_f32 v179, v179, v173, v173
	v_fma_f32 v180, v180, v173, v173
	v_fma_f32 v181, v181, v173, v173
	v_fma_f32 v182, v182, v173, v173
	v_fma_f32 v183, v183, v173, v173
	v_rcp_f32_e32 v176, v176
	v_rcp_f32_e32 v177, v177
	v_rcp_f32_e32 v178, v178
	v_rcp_f32_e32 v179, v179
	v_rcp_f32_e32 v180, v180
	v_rcp_f32_e32 v181, v181
	v_rcp_f32_e32 v182, v182
	v_rcp_f32_e32 v183, v183
	v_add_u32_e32 v202, 144, v159
	v_mad_i64_i32 v[202:203], s[0:1], v202, s48, v[204:205]
	v_mul_f32_e32 v184, v184, v176
	v_mul_f32_e32 v185, v185, v177
	v_mul_f32_e32 v186, v186, v178
	v_mul_f32_e32 v187, v187, v179
	v_mul_f32_e32 v188, v188, v180
	v_mul_f32_e32 v189, v189, v181
	v_mul_f32_e32 v190, v190, v182
	v_mul_f32_e32 v191, v191, v183
	v_lshl_add_u64 v[202:203], v[202:203], 0, v[206:207]
	v_cvt_pk_bf16_f32 v196, v184, v185
	v_cvt_pk_bf16_f32 v197, v186, v187
	v_cvt_pk_bf16_f32 v198, v188, v189
	v_cvt_pk_bf16_f32 v199, v190, v191
	global_store_dwordx4 v[202:203], v[196:199], off
	s_waitcnt lgkmcnt(1)
; __device__ __forceinline__ unsigned cvt_pk_bf16(float lo, float hi) { unsigned r; asm volatile("v_cvt_pk_bf16_f32 %0, %1, %2" : "=v"(r) : "v"(lo), "v"(hi)); return r; }
;     __device__ __forceinline__ void operator()(const f32x4 (&acc)[2][2][4][2], const Unit& u, int wr, int wc, int fr, int fq) const {
;     ...
;             for (int m = 0; m < 4; ++m) { const int row = row0 + ai * HALF + m * 16; const float rs = rsv[ai][m];
;                 float o[8];
;                 const float rs2 = -1.4426950408889634f * rs, rq = rs * rs;
; #pragma unroll
;                 for (int n = 0; n < 2; ++n)
; #pragma unroll
;                     for (int i = 0; i < 4; ++i) { const float a = acc[ai][0][m][n][i], b = acc[ai][1][m][n][i];
;                         const float e = __builtin_amdgcn_exp2f(a * rs2); o[n * 4 + i] = (a * b) * (rq * __builtin_amdgcn_rcpf(1.0f + e)); }
;                 u32x4 w; w.x = cvt_pk_bf16(o[0], o[1]); w.y = cvt_pk_bf16(o[2], o[3]); w.z = cvt_pk_bf16(o[4], o[5]); w.w = cvt_pk_bf16(o[6], o[7]);
;                 *(u32x4*)(O + (size_t)row * ldc + col0) = w; }
	v_mul_f32_e32 v172, 0xbfb8aa3b, v161
	v_mul_f32_e32 v173, v161, v161
	v_rcp_f32_e32 v173, v173
	v_mul_f32_e32 v176, v28, v172
	v_mul_f32_e32 v177, v29, v172
	v_mul_f32_e32 v178, v30, v172
	v_mul_f32_e32 v179, v31, v172
	v_mul_f32_e32 v180, v20, v172
	v_mul_f32_e32 v181, v21, v172
	v_mul_f32_e32 v182, v22, v172
	v_mul_f32_e32 v183, v23, v172
	v_exp_f32_e32 v176, v176
	v_exp_f32_e32 v177, v177
	v_exp_f32_e32 v178, v178
	v_exp_f32_e32 v179, v179
	v_exp_f32_e32 v180, v180
	v_exp_f32_e32 v181, v181
	v_exp_f32_e32 v182, v182
	v_exp_f32_e32 v183, v183
	v_mul_f32_e32 v184, v28, v24
	v_mul_f32_e32 v185, v29, v25
	v_mul_f32_e32 v186, v30, v26
	v_mul_f32_e32 v187, v31, v27
	v_mul_f32_e32 v188, v20, v16
	v_mul_f32_e32 v189, v21, v17
	v_mul_f32_e32 v190, v22, v18
	v_mul_f32_e32 v191, v23, v19
	v_fma_f32 v176, v176, v173, v173
	v_fma_f32 v177, v177, v173, v173
	v_fma_f32 v178, v178, v173, v173
	v_fma_f32 v179, v179, v173, v173
	v_fma_f32 v180, v180, v173, v173
	v_fma_f32 v181, v181, v173, v173
	v_fma_f32 v182, v182, v173, v173
	v_fma_f32 v183, v183, v173, v173
	v_rcp_f32_e32 v176, v176
	v_rcp_f32_e32 v177, v177
	v_rcp_f32_e32 v178, v178
	v_rcp_f32_e32 v179, v179
	v_rcp_f32_e32 v180, v180
	v_rcp_f32_e32 v181, v181
	v_rcp_f32_e32 v182, v182
	v_rcp_f32_e32 v183, v183
	v_add_u32_e32 v200, 160, v159
	v_mad_i64_i32 v[200:201], s[0:1], v200, s48, v[204:205]
	v_mul_f32_e32 v184, v184, v176
	v_mul_f32_e32 v185, v185, v177
	v_mul_f32_e32 v186, v186, v178
	v_mul_f32_e32 v187, v187, v179
	v_mul_f32_e32 v188, v188, v180
	v_mul_f32_e32 v189, v189, v181
	v_mul_f32_e32 v190, v190, v182
	v_mul_f32_e32 v191, v191, v183
	v_lshl_add_u64 v[200:201], v[200:201], 0, v[206:207]
	v_cvt_pk_bf16_f32 v192, v184, v185
	v_cvt_pk_bf16_f32 v193, v186, v187
	v_cvt_pk_bf16_f32 v194, v188, v189
	v_cvt_pk_bf16_f32 v195, v190, v191
	global_store_dwordx4 v[200:201], v[192:195], off
	s_waitcnt lgkmcnt(0)
	v_mul_f32_e32 v172, 0xbfb8aa3b, v232
	v_mul_f32_e32 v173, v232, v232
	v_rcp_f32_e32 v173, v173
	v_mul_f32_e32 v176, v12, v172
	v_mul_f32_e32 v177, v13, v172
	v_mul_f32_e32 v178, v14, v172
	v_mul_f32_e32 v179, v15, v172
	v_mul_f32_e32 v180, v4, v172
	v_mul_f32_e32 v181, v5, v172
	v_mul_f32_e32 v182, v6, v172
	v_mul_f32_e32 v183, v7, v172
	v_exp_f32_e32 v176, v176
	v_exp_f32_e32 v177, v177
	v_exp_f32_e32 v178, v178
	v_exp_f32_e32 v179, v179
	v_exp_f32_e32 v180, v180
	v_exp_f32_e32 v181, v181
	v_exp_f32_e32 v182, v182
	v_exp_f32_e32 v183, v183
	v_mul_f32_e32 v184, v12, v8
	v_mul_f32_e32 v185, v13, v9
	v_mul_f32_e32 v186, v14, v10
	v_mul_f32_e32 v187, v15, v11
	v_mul_f32_e32 v188, v4, v0
	v_mul_f32_e32 v189, v5, v1
	v_mul_f32_e32 v190, v6, v2
	v_mul_f32_e32 v191, v7, v3
	v_fma_f32 v176, v176, v173, v173
	v_fma_f32 v177, v177, v173, v173
	v_fma_f32 v178, v178, v173, v173
	v_fma_f32 v179, v179, v173, v173
	v_fma_f32 v180, v180, v173, v173
	v_fma_f32 v181, v181, v173, v173
	v_fma_f32 v182, v182, v173, v173
	v_fma_f32 v183, v183, v173, v173
	v_rcp_f32_e32 v176, v176
	v_rcp_f32_e32 v177, v177
	v_rcp_f32_e32 v178, v178
	v_rcp_f32_e32 v179, v179
	v_rcp_f32_e32 v180, v180
	v_rcp_f32_e32 v181, v181
	v_rcp_f32_e32 v182, v182
	v_rcp_f32_e32 v183, v183
	v_add_u32_e32 v202, 176, v159
	v_mad_i64_i32 v[202:203], s[0:1], v202, s48, v[204:205]
	v_mul_f32_e32 v184, v184, v176
	v_mul_f32_e32 v185, v185, v177
	v_mul_f32_e32 v186, v186, v178
	v_mul_f32_e32 v187, v187, v179
	v_mul_f32_e32 v188, v188, v180
	v_mul_f32_e32 v189, v189, v181
	v_mul_f32_e32 v190, v190, v182
	v_mul_f32_e32 v191, v191, v183
	v_lshl_add_u64 v[202:203], v[202:203], 0, v[206:207]
	v_cvt_pk_bf16_f32 v196, v184, v185
	v_cvt_pk_bf16_f32 v197, v186, v187
	v_cvt_pk_bf16_f32 v198, v188, v189
	v_cvt_pk_bf16_f32 v199, v190, v191
	global_store_dwordx4 v[202:203], v[196:199], off
	s_mov_b64 s[0:1], -1
	s_cbranch_vccnz .LBB0_3045
	s_andn2_b64 vcc, exec, s[12:13]
	s_cbranch_vccnz .LBB0_3044
	s_barrier
	s_branch .LBB0_3044
